# P5 GEMM-part exit: wave 1 warms the 16 KiB of S5 scan code that follow, stacked on v93
# speedup vs baseline: 1.0008x; 1.0004x over previous
.Lcpf_pc_t0:
	s_add_u32 s98, s98, .Lcpf_pc_t0-.Lcpf_pc_t0
	s_addc_u32 s99, s99, 0
	v_lshlrev_b32_e32 v252, 7, v186
	global_load_dword v253, v252, s[98:99]
	s_add_u32 s98, s98, 0x2000
	s_addc_u32 s99, s99, 0
	global_load_dword v253, v252, s[98:99]
.Lcpf_skip_t0:
	s_waitcnt vmcnt(0)
	v_readlane_b32 s44, v255, 48
	v_readlane_b32 s88, v255, 11
	v_readlane_b32 s97, v255, 4
	v_readlane_b32 s56, v255, 6
	v_readlane_b32 s57, v255, 9
	v_readlane_b32 s33, v255, 10
	v_readlane_b32 s36, v255, 27
	v_readlane_b32 s45, v255, 49
	v_readlane_b32 s89, v255, 12
	s_barrier
